# attention softmax: row max taken on raw scores so the cross-half ds_bpermute latency hides under the 32 v_exp; same decisions via exp of the max
# speedup vs baseline: 1.0047x; 1.0047x over previous
; __device__ __forceinline__ float max3f(float a, float b, float c) { float r; asm("v_max3_f32 %0, %1, %2, %3" : "=v"(r) : "v"(a), "v"(b), "v"(c)); return r; }
; __device__ __forceinline__ void attn_phase(KA a, lds8* lds, int tid, int lane, int wave) {
;     ...
;             for (int r = 0; r < 16; ++r) { s0[r] = __builtin_amdgcn_exp2f(s0[r]); s1[r] = __builtin_amdgcn_exp2f(s1[r]); }
;             float mx = max3f(s0[0], s1[0], s0[1]);
;             mx = max3f(mx, s1[1], s0[2]); mx = max3f(mx, s1[2], s0[3]); mx = max3f(mx, s1[3], s0[4]); mx = max3f(mx, s1[4], s0[5]); mx = max3f(mx, s1[5], s0[6]); mx = max3f(mx, s1[6], s0[7]); mx = max3f(mx, s1[7], s0[8]);
;             mx = max3f(mx, s1[8], s0[9]); mx = max3f(mx, s1[9], s0[10]); mx = max3f(mx, s1[10], s0[11]); mx = max3f(mx, s1[11], s0[12]); mx = max3f(mx, s1[12], s0[13]); mx = max3f(mx, s1[13], s0[14]); mx = max3f(mx, s1[14], s0[15]);
;             mx = fmaxf(mx, s1[15]);
;             mx = fmaxf(mx, __shfl_xor(mx, 32));
;             const bool mv = (mx > 256.0f) | (mx < 0.00390625f);
;             if (__any(mv)) { const float al = mv ? __builtin_amdgcn_rcpf(mx) : 1.0f; const float dl = mv ? __builtin_amdgcn_logf(mx) : 0.f;
;                 lsA *= al; lsB *= al; lsC *= al; lsD *= al;
; #pragma unroll
;                 for (int db = 0; db < 4; ++db) O[db] = O[db] * al;
;                 negm = negm - dl; s0 = s0 * al; s1 = s1 * al; }
.LBB0_1310:
	s_nop 9
	v_max3_f32 v235, v96, v80, v97
	v_max3_f32 v235, v235, v81, v98
	v_max3_f32 v235, v235, v82, v99
	v_max3_f32 v235, v235, v83, v100
	v_max3_f32 v235, v235, v84, v101
	v_max3_f32 v235, v235, v85, v102
	v_max3_f32 v235, v235, v86, v103
	v_max3_f32 v235, v235, v87, v104
	v_max3_f32 v235, v235, v88, v105
	v_max3_f32 v235, v235, v89, v106
	v_max3_f32 v235, v235, v90, v107
	v_max3_f32 v235, v235, v91, v108
	v_max3_f32 v235, v235, v92, v109
	v_max3_f32 v235, v235, v93, v110
	v_max3_f32 v235, v235, v94, v111
	v_max_f32_e32 v235, v235, v95
	v_xor_b32_e32 v251, 32, v248
	v_lshlrev_b32_e32 v251, 2, v251
	ds_bpermute_b32 v249, v251, v235
	v_exp_f32_e32 v224, v96
	v_exp_f32_e32 v80, v80
	v_exp_f32_e32 v225, v97
	v_exp_f32_e32 v220, v84
	v_exp_f32_e32 v84, v88
	v_exp_f32_e32 v81, v81
	v_exp_f32_e32 v226, v98
	v_exp_f32_e32 v82, v82
	v_exp_f32_e32 v227, v99
	v_exp_f32_e32 v83, v83
	v_exp_f32_e32 v228, v100
	v_exp_f32_e32 v229, v101
	v_exp_f32_e32 v221, v85
	v_exp_f32_e32 v230, v102
	v_exp_f32_e32 v222, v86
	v_exp_f32_e32 v231, v103
	v_exp_f32_e32 v223, v87
	v_exp_f32_e32 v100, v104
	v_exp_f32_e32 v101, v105
	v_exp_f32_e32 v85, v89
	v_exp_f32_e32 v102, v106
	v_exp_f32_e32 v86, v90
	v_exp_f32_e32 v103, v107
	v_exp_f32_e32 v87, v91
	v_exp_f32_e32 v104, v108
	v_mov_b32_e32 v108, v251
	v_exp_f32_e32 v98, v92
	v_exp_f32_e32 v105, v109
	v_exp_f32_e32 v97, v95
	v_exp_f32_e32 v99, v93
	v_exp_f32_e32 v106, v110
	v_exp_f32_e32 v96, v94
	v_exp_f32_e32 v107, v111
	s_waitcnt lgkmcnt(0)
	v_max_f32_e32 v235, v235, v249
	v_exp_f32_e32 v88, v235
	s_nop 0
	v_cmp_lt_f32_e32 vcc, s40, v88
	v_cmp_gt_f32_e64 s[14:15], s41, v88
	s_or_b64 vcc, vcc, s[14:15]
	s_cbranch_vccz .LBB0_1312
	v_rcp_f32_e32 v89, v88
	v_log_f32_e32 v90, v88
	v_cndmask_b32_e32 v88, 1.0, v89, vcc
	v_pk_mul_f32 v[62:63], v[62:63], v[88:89] op_sel_hi:[1,0]
	v_pk_mul_f32 v[60:61], v[60:61], v[88:89] op_sel_hi:[1,0]
	v_pk_mul_f32 v[58:59], v[58:59], v[88:89] op_sel_hi:[1,0]
	v_pk_mul_f32 v[56:57], v[56:57], v[88:89] op_sel_hi:[1,0]
	v_pk_mul_f32 v[54:55], v[54:55], v[88:89] op_sel_hi:[1,0]
	v_pk_mul_f32 v[52:53], v[52:53], v[88:89] op_sel_hi:[1,0]
	v_pk_mul_f32 v[50:51], v[50:51], v[88:89] op_sel_hi:[1,0]
	v_pk_mul_f32 v[48:49], v[48:49], v[88:89] op_sel_hi:[1,0]
	v_pk_mul_f32 v[46:47], v[46:47], v[88:89] op_sel_hi:[1,0]
	v_pk_mul_f32 v[44:45], v[44:45], v[88:89] op_sel_hi:[1,0]
	v_pk_mul_f32 v[42:43], v[42:43], v[88:89] op_sel_hi:[1,0]
	v_pk_mul_f32 v[40:41], v[40:41], v[88:89] op_sel_hi:[1,0]
	v_pk_mul_f32 v[38:39], v[38:39], v[88:89] op_sel_hi:[1,0]
	v_pk_mul_f32 v[36:37], v[36:37], v[88:89] op_sel_hi:[1,0]
	v_pk_mul_f32 v[34:35], v[34:35], v[88:89] op_sel_hi:[1,0]
	v_pk_mul_f32 v[32:33], v[32:33], v[88:89] op_sel_hi:[1,0]
	v_pk_mul_f32 v[30:31], v[30:31], v[88:89] op_sel_hi:[1,0]
	v_pk_mul_f32 v[28:29], v[28:29], v[88:89] op_sel_hi:[1,0]
	v_pk_mul_f32 v[26:27], v[26:27], v[88:89] op_sel_hi:[1,0]
	v_pk_mul_f32 v[24:25], v[24:25], v[88:89] op_sel_hi:[1,0]
	v_pk_mul_f32 v[22:23], v[22:23], v[88:89] op_sel_hi:[1,0]
	v_pk_mul_f32 v[20:21], v[20:21], v[88:89] op_sel_hi:[1,0]
	v_pk_mul_f32 v[18:19], v[18:19], v[88:89] op_sel_hi:[1,0]
	v_pk_mul_f32 v[16:17], v[16:17], v[88:89] op_sel_hi:[1,0]
	v_pk_mul_f32 v[14:15], v[14:15], v[88:89] op_sel_hi:[1,0]
	v_pk_mul_f32 v[12:13], v[12:13], v[88:89] op_sel_hi:[1,0]
	v_pk_mul_f32 v[10:11], v[10:11], v[88:89] op_sel_hi:[1,0]
	v_pk_mul_f32 v[8:9], v[8:9], v[88:89] op_sel_hi:[1,0]
	v_pk_mul_f32 v[6:7], v[6:7], v[88:89] op_sel_hi:[1,0]
	v_pk_mul_f32 v[4:5], v[4:5], v[88:89] op_sel_hi:[1,0]
	v_pk_mul_f32 v[2:3], v[2:3], v[88:89] op_sel_hi:[1,0]
	v_pk_mul_f32 v[0:1], v[0:1], v[88:89] op_sel_hi:[1,0]
	v_cndmask_b32_e32 v89, 0, v90, vcc
	v_pk_mul_f32 v[210:211], v[210:211], v[88:89] op_sel_hi:[1,0]
	v_pk_mul_f32 v[208:209], v[208:209], v[88:89] op_sel_hi:[1,0]
	v_sub_f32_e32 v79, v79, v89
	v_sub_f32_e32 v78, v78, v89
	v_sub_f32_e32 v77, v77, v89
	v_sub_f32_e32 v76, v76, v89
	v_sub_f32_e32 v75, v75, v89
	v_sub_f32_e32 v74, v74, v89
	v_sub_f32_e32 v73, v73, v89
	v_sub_f32_e32 v72, v72, v89
	v_sub_f32_e32 v71, v71, v89
	v_sub_f32_e32 v70, v70, v89
	v_sub_f32_e32 v69, v69, v89
	v_sub_f32_e32 v68, v68, v89
	v_sub_f32_e32 v67, v67, v89
	v_sub_f32_e32 v66, v66, v89
	v_sub_f32_e32 v65, v65, v89
	v_sub_f32_e32 v64, v64, v89
	v_pk_mul_f32 v[106:107], v[106:107], v[88:89] op_sel_hi:[1,0]
	v_pk_mul_f32 v[104:105], v[104:105], v[88:89] op_sel_hi:[1,0]
	v_pk_mul_f32 v[102:103], v[102:103], v[88:89] op_sel_hi:[1,0]
	v_pk_mul_f32 v[100:101], v[100:101], v[88:89] op_sel_hi:[1,0]
	v_pk_mul_f32 v[230:231], v[230:231], v[88:89] op_sel_hi:[1,0]
	v_pk_mul_f32 v[228:229], v[228:229], v[88:89] op_sel_hi:[1,0]
	v_pk_mul_f32 v[226:227], v[226:227], v[88:89] op_sel_hi:[1,0]
	v_pk_mul_f32 v[224:225], v[224:225], v[88:89] op_sel_hi:[1,0]
	v_pk_mul_f32 v[96:97], v[96:97], v[88:89] op_sel_hi:[1,0]
	v_pk_mul_f32 v[98:99], v[98:99], v[88:89] op_sel_hi:[1,0]
	v_pk_mul_f32 v[86:87], v[86:87], v[88:89] op_sel_hi:[1,0]
	v_pk_mul_f32 v[84:85], v[84:85], v[88:89] op_sel_hi:[1,0]
	v_pk_mul_f32 v[222:223], v[222:223], v[88:89] op_sel_hi:[1,0]
	v_pk_mul_f32 v[220:221], v[220:221], v[88:89] op_sel_hi:[1,0]
	v_pk_mul_f32 v[82:83], v[82:83], v[88:89] op_sel_hi:[1,0]
	v_pk_mul_f32 v[80:81], v[80:81], v[88:89] op_sel_hi:[1,0]
